# mla_rows: dropped the loop-top vmcnt(0) that only drained the previous rows' stores (all loads already complete on every back-edge path), so the next rows' loads issue under the store acks
# speedup vs baseline: 1.0058x; 1.0058x over previous
; __device__ __forceinline__ float lane_xor(float v, int lane, int o) { return __builtin_bit_cast(float, __builtin_amdgcn_ds_bpermute((lane ^ o) << 2, __builtin_bit_cast(int, v))); }
; __device__ __forceinline__ void mla_rows(const bf16_t* U, const float* gcq, const float* gckv, const float* rope, bf16_t* XQ, bf16_t* XKV, bf16_t* KC, int gw, int ngw) {
;     ...
;     for (int r0 = gw; r0 < MROWS; r0 += 2 * ngw) {
;         u32x2 cq[2]; unsigned ckv[2]; float krv[2], cs[2], sn[2]; int rr[2];
; #pragma unroll
;         for (int k = 0; k < 2; ++k) { int r = r0 + k * ngw; r = r < MROWS ? r : r0; rr[k] = r;
;             const bf16_t* up = U + (size_t)r * DIN + 2048;
;             cq[k] = *(const u32x2*)(up + 4 * lane); ckv[k] = *(const unsigned*)(up + 256 + 2 * lane); krv[k] = bf2f(up[384 + (lane & 31)]);
;             const int s = r % LP, j = lane & 15; cs[k] = rope[(size_t)s * 32 + j]; sn[k] = rope[(size_t)s * 32 + 16 + j]; }
; #pragma unroll
;         for (int k = 0; k < 2; ++k) {
;             if (k == 1 && r0 + ngw >= MROWS) break;
;             const int r = rr[k];
;             const float q0 = __builtin_bit_cast(float, cq[k].x << 16), q1 = __builtin_bit_cast(float, cq[k].x & 0xffff0000u), q2 = __builtin_bit_cast(float, cq[k].y << 16), q3 = __builtin_bit_cast(float, cq[k].y & 0xffff0000u);
;             const float k0 = __builtin_bit_cast(float, ckv[k] << 16), k1 = __builtin_bit_cast(float, ckv[k] & 0xffff0000u);
;             const float sq = wave_sum((q0 * q0 + q1 * q1) + (q2 * q2 + q3 * q3), lane), sk = wave_sum(k0 * k0 + k1 * k1, lane);
;             const float rq = 1.0f / sqrtf(sq * (1.0f / 256.0f) + EPSN), rk = 1.0f / sqrtf(sk * (1.0f / 128.0f) + EPSN);
;             u32x2 wq; wq.x = pk2(q0 * rq * gq.x, q1 * rq * gq.y); wq.y = pk2(q2 * rq * gq.z, q3 * rq * gq.w);
;             *(u32x2*)(XQ + (size_t)r * 256 + 4 * lane) = wq;
;             *(unsigned*)(XKV + (size_t)r * 128 + 2 * lane) = pk2(k0 * rk * gk0, k1 * rk * gk1);
;             const float other = lane_xor(krv[k], lane, 16);
;             const float ro = (lane & 16) ? (krv[k] * cs[k] + other * sn[k]) : (krv[k] * cs[k] - other * sn[k]);
;             if (lane < 32) { const unsigned short ob = (unsigned short)f2bf(ro); bf16_t* kc = KC + (size_t)r * 384 + 64 + lane;
;                 kc[0] = ob; kc[96] = ob; kc[192] = ob; kc[288] = ob; }
.LBB0_642:
	s_ashr_i32 s15, s14, 31
	s_mul_i32 s6, s14, 0x1340
	s_mul_hi_i32 s7, s14, 0x1340
	s_add_u32 s6, s16, s6
	s_addc_u32 s7, s17, s7
	v_mov_b32_e32 v19, v1
	s_waitcnt lgkmcnt(0)
	v_lshl_add_u64 v[20:21], s[6:7], 0, v[18:19]
	s_movk_i32 s30, 0x1000
	s_add_u32 s8, s6, 0x1000
	v_add_co_u32_e32 v20, vcc, s30, v20
	s_addc_u32 s9, s7, 0
	v_mov_b32_e32 v17, v1
	v_addc_co_u32_e32 v21, vcc, 0, v21, vcc
	flat_load_dword v22, v[20:21] offset:512
	v_lshl_add_u64 v[20:21], s[8:9], 0, v[16:17]
	flat_load_dwordx2 v[24:25], v[20:21]
	s_mul_hi_i32 s6, s14, 0x7e07e07f
	s_lshr_b32 s7, s6, 31
	s_ashr_i32 s6, s6, 12
	s_add_i32 s6, s6, s7
	s_mulk_i32 s6, 0x2080
	v_lshl_add_u64 v[20:21], s[8:9], 0, v[0:1]
	s_sub_i32 s6, s14, s6
	flat_load_ushort v44, v[20:21] offset:768
	s_ashr_i32 s7, s6, 31
	s_add_i32 s27, s14, s26
	s_lshl_b64 s[6:7], s[6:7], 7
	s_cmp_lt_i32 s27, 0x14500
	s_cselect_b32 s8, s27, s14
	v_lshl_add_u64 v[26:27], v[8:9], 0, s[6:7]
	s_mul_i32 s6, s8, 0x1340
	s_mul_hi_i32 s7, s8, 0x1340
	s_add_u32 s6, s16, s6
	s_addc_u32 s7, s17, s7
	v_lshl_add_u64 v[20:21], s[6:7], 0, v[18:19]
	v_add_co_u32_e32 v36, vcc, s30, v20
	s_add_u32 s10, s6, 0x1000
	s_nop 0
	v_addc_co_u32_e32 v37, vcc, 0, v21, vcc
	s_addc_u32 s11, s7, 0
	s_mul_hi_i32 s9, s8, 0x7e07e07f
	s_lshr_b32 s6, s9, 31
	s_ashr_i32 s7, s9, 12
	s_add_i32 s6, s7, s6
	s_mulk_i32 s6, 0x2080
	s_sub_i32 s6, s8, s6
	s_ashr_i32 s7, s6, 31
	s_lshl_b64 s[6:7], s[6:7], 7
	v_lshl_add_u64 v[40:41], s[10:11], 0, v[0:1]
	s_waitcnt vmcnt(0) lgkmcnt(0)
	v_lshlrev_b32_e32 v20, 16, v22
	v_and_b32_e32 v21, 0xffff0000, v22
	v_lshlrev_b32_e32 v23, 16, v25
	v_lshlrev_b32_e32 v22, 16, v24
	v_and_b32_e32 v25, 0xffff0000, v25
	v_and_b32_e32 v24, 0xffff0000, v24
	v_pk_mul_f32 v[34:35], v[20:21], v[20:21]
	v_pk_mul_f32 v[38:39], v[24:25], v[24:25]
	v_add_f32_e32 v19, v34, v35
	v_pk_fma_f32 v[34:35], v[22:23], v[22:23], v[38:39]
	ds_bpermute_b32 v38, v28, v19
	v_add_f32_e32 v34, v34, v35
	ds_bpermute_b32 v35, v28, v34
	s_waitcnt lgkmcnt(1)
	v_add_f32_e32 v19, v19, v38
	ds_bpermute_b32 v42, v29, v19
	s_waitcnt lgkmcnt(1)
	v_add_f32_e32 v34, v34, v35
	ds_bpermute_b32 v35, v29, v34
	v_lshl_add_u64 v[38:39], s[10:11], 0, v[16:17]
	s_waitcnt lgkmcnt(1)
	v_add_f32_e32 v17, v19, v42
	ds_bpermute_b32 v19, v30, v17
	s_waitcnt lgkmcnt(1)
	v_add_f32_e32 v34, v34, v35
	ds_bpermute_b32 v35, v30, v34
	v_lshl_add_u64 v[42:43], v[8:9], 0, s[6:7]
	s_mov_b32 s6, 0xf800000
	s_waitcnt lgkmcnt(1)
	v_add_f32_e32 v17, v17, v19
	ds_bpermute_b32 v19, v31, v17
	s_waitcnt lgkmcnt(1)
	v_add_f32_e32 v34, v34, v35
	ds_bpermute_b32 v35, v31, v34
	s_waitcnt lgkmcnt(1)
	v_add_f32_e32 v17, v17, v19
	ds_bpermute_b32 v19, v32, v17
	s_waitcnt lgkmcnt(1)
	v_add_f32_e32 v34, v34, v35
	ds_bpermute_b32 v35, v32, v34
	s_waitcnt lgkmcnt(1)
	v_add_f32_e32 v45, v17, v19
	ds_bpermute_b32 v46, v33, v45
	s_waitcnt lgkmcnt(1)
	v_add_f32_e32 v47, v34, v35
	flat_load_dword v34, v[26:27]
	flat_load_dword v35, v[26:27] offset:64
	s_nop 0
	flat_load_dwordx2 v[26:27], v[38:39]
	s_nop 0
	flat_load_dword v36, v[36:37] offset:512
	s_nop 0
	flat_load_ushort v37, v[40:41] offset:768
	flat_load_dword v17, v[42:43]
	flat_load_dword v19, v[42:43] offset:64
	ds_bpermute_b32 v48, v33, v47
	v_lshlrev_b32_e32 v38, 16, v44
	s_waitcnt lgkmcnt(0)
	v_add_f32_e32 v39, v45, v46
	v_fmamk_f32 v39, v39, 0x3c000000, v218
	v_mul_f32_e32 v41, 0x4f800000, v39
	v_add_f32_e32 v40, v47, v48
	v_cmp_gt_f32_e32 vcc, s6, v39
	v_fmamk_f32 v40, v40, 0x3b800000, v218
	v_cmp_gt_f32_e64 s[6:7], s6, v40
	v_cndmask_b32_e32 v39, v39, v41, vcc
	v_mul_f32_e32 v41, 0x4f800000, v40
	v_sqrt_f32_e32 v42, v39
	v_cndmask_b32_e64 v40, v40, v41, s[6:7]
	v_sqrt_f32_e32 v41, v40
	v_add_u32_e32 v43, -1, v42
	v_add_u32_e32 v44, 1, v42
	v_fma_f32 v45, -v43, v42, v39
	v_fma_f32 v46, -v44, v42, v39
	v_add_u32_e32 v47, -1, v41
	v_cmp_ge_f32_e64 s[10:11], 0, v45
	v_add_u32_e32 v48, 1, v41
	v_fma_f32 v45, -v48, v41, v40
	v_cndmask_b32_e64 v42, v42, v43, s[10:11]
	v_fma_f32 v43, -v47, v41, v40
	v_cmp_lt_f32_e64 s[10:11], 0, v46
	s_nop 1
	v_cndmask_b32_e64 v42, v42, v44, s[10:11]
	v_cmp_ge_f32_e64 s[10:11], 0, v43
	v_mul_f32_e32 v43, 0x37800000, v42
	v_cndmask_b32_e32 v42, v42, v43, vcc
	v_cndmask_b32_e64 v41, v41, v47, s[10:11]
	v_cmp_lt_f32_e64 s[10:11], 0, v45
	v_mov_b32_e32 v47, 0x260
	s_nop 0
	v_cndmask_b32_e64 v41, v41, v48, s[10:11]
	v_mul_f32_e32 v44, 0x37800000, v41
	v_cndmask_b32_e64 v41, v41, v44, s[6:7]
	v_cmp_class_f32_e64 s[6:7], v40, v47
	s_nop 1
	v_cndmask_b32_e64 v40, v41, v40, s[6:7]
	v_div_scale_f32 v41, s[6:7], v40, v40, 1.0
	v_rcp_f32_e32 v44, v41
	v_div_scale_f32 v43, vcc, 1.0, v40, 1.0
	v_fma_f32 v45, -v41, v44, 1.0
	v_fmac_f32_e32 v44, v45, v44
	v_mul_f32_e32 v45, v43, v44
	v_fma_f32 v46, -v41, v45, v43
	v_fmac_f32_e32 v45, v46, v44
	v_fma_f32 v41, -v41, v45, v43
	v_div_fmas_f32 v41, v41, v44, v45
	v_div_fixup_f32 v40, v41, v40, 1.0
	v_pk_mul_f32 v[22:23], v[40:41], v[22:23] op_sel_hi:[0,1]
	v_pk_mul_f32 v[22:23], v[2:3], v[22:23]
	v_cmp_class_f32_e32 vcc, v39, v47
	v_pk_mul_f32 v[24:25], v[40:41], v[24:25] op_sel_hi:[0,1]
	v_and_b32_sdwa v40, v23, v219 dst_sel:DWORD dst_unused:UNUSED_PAD src0_sel:WORD_1 src1_sel:DWORD
	v_cndmask_b32_e32 v39, v42, v39, vcc
	v_pk_mul_f32 v[24:25], v[14:15], v[24:25]
	v_and_b32_sdwa v41, v22, v219 dst_sel:DWORD dst_unused:UNUSED_PAD src0_sel:WORD_1 src1_sel:DWORD
	v_add3_u32 v23, v23, v40, s44
	v_div_scale_f32 v40, s[6:7], v39, v39, 1.0
	v_and_b32_sdwa v43, v25, v219 dst_sel:DWORD dst_unused:UNUSED_PAD src0_sel:WORD_1 src1_sel:DWORD
	v_and_b32_sdwa v44, v24, v219 dst_sel:DWORD dst_unused:UNUSED_PAD src0_sel:WORD_1 src1_sel:DWORD
	v_add3_u32 v22, v22, v41, s44
	v_rcp_f32_e32 v41, v40
	v_add3_u32 v25, v25, v43, s44
	v_add3_u32 v24, v24, v44, s44
	v_and_b32_e32 v25, 0xffff0000, v25
	v_and_b32_e32 v24, 0xffff0000, v24
	s_lshl_b64 s[6:7], s[14:15], 9
	v_or_b32_sdwa v23, v25, v23 dst_sel:DWORD dst_unused:UNUSED_PAD src0_sel:DWORD src1_sel:WORD_1
	v_or_b32_sdwa v22, v24, v22 dst_sel:DWORD dst_unused:UNUSED_PAD src0_sel:DWORD src1_sel:WORD_1
	v_lshl_add_u64 v[24:25], v[12:13], 0, s[6:7]
	flat_store_dwordx2 v[24:25], v[22:23]
	v_fma_f32 v22, -v40, v41, 1.0
	v_fmac_f32_e32 v41, v22, v41
	v_div_scale_f32 v22, vcc, 1.0, v39, 1.0
	v_mul_f32_e32 v23, v22, v41
	v_fma_f32 v24, -v40, v23, v22
	v_fmac_f32_e32 v23, v24, v41
	v_fma_f32 v22, -v40, v23, v22
	v_div_fmas_f32 v22, v22, v41, v23
	v_div_fixup_f32 v22, v22, v39, 1.0
	v_pk_mul_f32 v[20:21], v[22:23], v[20:21] op_sel_hi:[0,1]
	v_pk_mul_f32 v[20:21], v[6:7], v[20:21]
	s_lshl_b64 s[6:7], s[14:15], 8
	v_and_b32_sdwa v23, v20, v219 dst_sel:DWORD dst_unused:UNUSED_PAD src0_sel:WORD_1 src1_sel:DWORD
	v_and_b32_sdwa v22, v21, v219 dst_sel:DWORD dst_unused:UNUSED_PAD src0_sel:WORD_1 src1_sel:DWORD
	v_add3_u32 v20, v20, v23, s44
	v_add3_u32 v21, v21, v22, s44
	v_lshrrev_b32_e32 v22, 16, v20
	ds_bpermute_b32 v20, v32, v38
	v_and_or_b32 v21, v21, s49, v22
	v_lshl_add_u64 v[22:23], v[10:11], 0, s[6:7]
	flat_store_dword v[22:23], v21
	s_and_saveexec_b64 s[6:7], s[4:5]
	s_cbranch_execnz .LBB0_644
; __device__ __forceinline__ void mla_rows(const bf16_t* U, const float* gcq, const float* gckv, const float* rope, bf16_t* XQ, bf16_t* XKV, bf16_t* KC, int gw, int ngw) {
;     ...
;     for (int r0 = gw; r0 < MROWS; r0 += 2 * ngw) {
;         u32x2 cq[2]; unsigned ckv[2]; float krv[2], cs[2], sn[2]; int rr[2];
; #pragma unroll
;         for (int k = 0; k < 2; ++k) { int r = r0 + k * ngw; r = r < MROWS ? r : r0; rr[k] = r;
;             const bf16_t* up = U + (size_t)r * DIN + 2048;
;             cq[k] = *(const u32x2*)(up + 4 * lane); ckv[k] = *(const unsigned*)(up + 256 + 2 * lane); krv[k] = bf2f(up[384 + (lane & 31)]);
;             const int s = r % LP, j = lane & 15; cs[k] = rope[(size_t)s * 32 + j]; sn[k] = rope[(size_t)s * 32 + 16 + j]; }
; #pragma unroll
;         for (int k = 0; k < 2; ++k) {
;             if (k == 1 && r0 + ngw >= MROWS) break;
	s_or_b64 exec, exec, s[6:7]
	s_cmp_gt_i32 s27, 0x144ff
	s_cbranch_scc1 .LBB0_641
	s_branch .LBB0_645
